# attention stack: v7 + two-chain row sums + K-fragment read hoist
# baseline (speedup 1.0000x reference)
.Latt_prio_done:
.LBB0_674:
	s_add_i32 s70, s67, 1
	s_and_b32 s69, s70, 3
	s_mul_i32 s2, s69, 0x3400
	v_add_u32_e32 v0, s2, v196
	ds_read_b128 v[2:5], v0
	ds_read_b128 v[6:9], v0 offset:6656
	s_add_i32 s2, s67, -1
	s_and_b32 s2, s2, 3
	s_mulk_i32 s2, 0x3400
	s_and_b32 s71, s67, 2
	s_add_i32 s2, s2, 0
	s_xor_b32 s3, s71, 2
	v_add_u32_e32 v96, s2, v192
	s_mulk_i32 s3, 0x2400
	s_waitcnt vmcnt(5)
	ds_write_b128 v96, v[152:155]
	v_add_u32_e32 v96, s2, v185
	s_add_i32 s2, s67, 5
	s_waitcnt vmcnt(4)
	ds_write_b128 v96, v[156:159] offset:128
	v_add_u32_e32 v96, s3, v193
	s_min_i32 s46, s2, s66
	s_add_i32 s2, s67, 4
	v_add_u32_e32 v96, 0xd000, v96
	s_min_i32 s2, s2, s66
	s_lshl_b64 s[4:5], s[46:47], 16
	s_mov_b32 s3, s47
	s_waitcnt vmcnt(3)
	ds_write2_b64 v96, v[172:173], v[174:175] offset1:2
	v_lshl_add_u64 v[98:99], v[186:187], 0, s[4:5]
	s_lshl_b64 s[4:5], s[46:47], 12
	s_lshl_b64 s[2:3], s[2:3], 7
	v_lshl_add_u64 v[100:101], v[188:189], 0, s[4:5]
	global_load_dwordx4 v[152:155], v[98:99], off
	global_load_dwordx4 v[156:159], v[100:101], off
	v_lshl_add_u64 v[98:99], v[190:191], 0, s[2:3]
	global_load_dwordx4 v[172:175], v[98:99], off
	s_cmp_gt_i32 s67, s65
	s_cbranch_scc1 .LBB0_685
	s_waitcnt lgkmcnt(1)
	v_mfma_f32_32x32x16_bf16 v[112:127], v[2:5], v[128:131], v[48:63]
	ds_read_b128 v[10:13], v0 offset:32
	ds_read_b128 v[202:205], v0 offset:6688
	v_add_f32_e32 v211, 0, v80
	v_add_f32_e32 v210, 0, v81
	v_cvt_pk_bf16_f32 v176, v80, v81
	s_waitcnt lgkmcnt(2)
	v_mfma_f32_32x32x16_bf16 v[96:111], v[6:9], v[128:131], v[48:63]
	v_add_f32_e32 v211, v82, v211
	v_add_f32_e32 v210, v83, v210
	v_add_f32_e32 v211, v84, v211
	v_cvt_pk_bf16_f32 v177, v82, v83
	s_waitcnt lgkmcnt(1)
	v_mfma_f32_32x32x16_bf16 v[112:127], v[10:13], v[132:135], v[112:127]
	ds_read_b128 v[2:5], v0 offset:64
	ds_read_b128 v[6:9], v0 offset:6720
	v_add_f32_e32 v210, v85, v210
	v_add_f32_e32 v211, v86, v211
	v_add_f32_e32 v210, v87, v210
	v_cvt_pk_bf16_f32 v178, v84, v85
	v_cvt_pk_bf16_f32 v179, v86, v87
	s_waitcnt lgkmcnt(2)
	v_mfma_f32_32x32x16_bf16 v[96:111], v[202:205], v[132:135], v[96:111]
	v_add_f32_e32 v211, v88, v211
	v_add_f32_e32 v210, v89, v210
	v_cvt_pk_bf16_f32 v10, v88, v89
	s_waitcnt lgkmcnt(1)
	v_mfma_f32_32x32x16_bf16 v[112:127], v[2:5], v[136:139], v[112:127]
	ds_read_b128 v[80:83], v0 offset:96
	ds_read_b128 v[202:205], v0 offset:6752
	v_add_f32_e32 v211, v90, v211
	v_add_f32_e32 v210, v91, v210
	v_add_f32_e32 v211, v92, v211
	v_cvt_pk_bf16_f32 v11, v90, v91
	s_waitcnt lgkmcnt(2)
	v_mfma_f32_32x32x16_bf16 v[96:111], v[6:9], v[136:139], v[96:111]
	v_add_f32_e32 v210, v93, v210
	v_add_f32_e32 v211, v94, v211
	v_add_f32_e32 v210, v95, v210
	v_cvt_pk_bf16_f32 v12, v92, v93
	v_cvt_pk_bf16_f32 v13, v94, v95
	s_waitcnt lgkmcnt(1)
	v_mfma_f32_32x32x16_bf16 v[112:127], v[80:83], v[140:143], v[112:127]
	ds_read_b128 v[2:5], v0 offset:128
	ds_read_b128 v[206:209], v0 offset:6784
	v_add_f32_e32 v211, v16, v211
	v_add_f32_e32 v210, v17, v210
	v_cvt_pk_bf16_f32 v6, v16, v17
	s_waitcnt lgkmcnt(2)
	v_mfma_f32_32x32x16_bf16 v[96:111], v[202:205], v[140:143], v[96:111]
	v_add_f32_e32 v211, v18, v211
	v_add_f32_e32 v210, v19, v210
	v_add_f32_e32 v211, v20, v211
	v_cvt_pk_bf16_f32 v7, v18, v19
	s_waitcnt lgkmcnt(1)
	v_mfma_f32_32x32x16_bf16 v[112:127], v[2:5], v[144:147], v[112:127]
	ds_read_b128 v[14:17], v0 offset:160
	ds_read_b128 v[80:83], v0 offset:6816
	v_add_f32_e32 v210, v21, v210
	v_add_f32_e32 v211, v22, v211
	v_add_f32_e32 v210, v23, v210
	v_cvt_pk_bf16_f32 v8, v20, v21
	v_cvt_pk_bf16_f32 v9, v22, v23
	s_waitcnt lgkmcnt(2)
	v_mfma_f32_32x32x16_bf16 v[96:111], v[206:209], v[144:147], v[96:111]
	v_add_f32_e32 v211, v24, v211
	v_add_f32_e32 v210, v25, v210
	v_cvt_pk_bf16_f32 v2, v24, v25
	s_waitcnt lgkmcnt(1)
	v_mfma_f32_32x32x16_bf16 v[112:127], v[14:17], v[148:151], v[112:127]
	v_add_f32_e32 v211, v26, v211
	v_add_f32_e32 v210, v27, v210
	v_add_f32_e32 v211, v28, v211
	v_cvt_pk_bf16_f32 v3, v26, v27
	s_waitcnt lgkmcnt(0)
	v_mfma_f32_32x32x16_bf16 v[96:111], v[80:83], v[148:151], v[96:111]
	v_add_f32_e32 v210, v29, v210
	v_add_f32_e32 v211, v30, v211
	v_add_f32_e32 v210, v31, v210
	v_add_f32_e32 v0, v210, v211
	v_cvt_pk_bf16_f32 v4, v28, v29
	v_cvt_pk_bf16_f32 v5, v30, v31
	s_mul_i32 s4, s71, 0x2400
	v_add_u32_e32 v206, s4, v200
	ds_read_b128 v[16:19], v206 offset:53248
	ds_read_b128 v[202:205], v206 offset:57856
	s_cmp_ge_i32 s67, s65
	v_add_f32_e32 v201, v201, v0
	s_cbranch_scc1 .LBB0_682
	s_sub_i32 s2, s68, 64
	s_cmp_le_i32 s2, s63
	s_cbranch_scc1 .LBB0_680
	v_add_u32_e32 v0, s68, v197
	v_add_u32_e32 v15, 0xffffffa1, v0
	v_add_u32_e32 v14, 0xffffff81, v0
	v_cmp_le_i32_e64 s[2:3], v15, v184
	v_cmp_le_i32_e32 vcc, v14, v184
	s_nop 0
	v_cndmask_b32_e64 v96, v194, v96, s[2:3]
	v_cmp_lt_i32_e64 s[2:3], v14, v184
	v_add_u32_e32 v14, 0xffffffa2, v0
	v_cmp_le_i32_e64 s[4:5], v14, v184
	v_add_u32_e32 v14, 0xffffff83, v0
	s_nop 0
	v_cndmask_b32_e64 v97, v194, v97, s[4:5]
	v_cmp_le_i32_e64 s[4:5], v14, v184
	v_add_u32_e32 v14, 0xffffffa3, v0
	v_cmp_le_i32_e64 s[6:7], v14, v184
	v_add_u32_e32 v14, 0xffffff84, v0
	s_nop 0
	v_cndmask_b32_e64 v98, v194, v98, s[6:7]
	v_cmp_le_i32_e64 s[6:7], v14, v184
	v_add_u32_e32 v14, 0xffffffa4, v0
	v_cmp_le_i32_e64 s[8:9], v14, v184
	v_add_u32_e32 v14, 0xffffff89, v0
	s_nop 0
	v_cndmask_b32_e64 v99, v194, v99, s[8:9]
	v_cmp_le_i32_e64 s[8:9], v14, v184
	v_add_u32_e32 v14, 0xffffffa9, v0
	v_cmp_le_i32_e64 s[10:11], v14, v184
	v_add_u32_e32 v14, 0xffffff8a, v0
	s_nop 0
	v_cndmask_b32_e64 v100, v194, v100, s[10:11]
	v_cmp_le_i32_e64 s[10:11], v14, v184
	v_add_u32_e32 v14, 0xffffffaa, v0
	v_cmp_le_i32_e64 s[12:13], v14, v184
	v_add_u32_e32 v14, 0xffffff8b, v0
	s_nop 0
	v_cndmask_b32_e64 v101, v194, v101, s[12:13]
	v_cmp_le_i32_e64 s[12:13], v14, v184
	v_add_u32_e32 v14, 0xffffffab, v0
	v_cmp_le_i32_e64 s[14:15], v14, v184
	v_add_u32_e32 v14, 0xffffff8c, v0
	s_nop 0
	v_cndmask_b32_e64 v102, v194, v102, s[14:15]
	v_cmp_le_i32_e64 s[14:15], v14, v184
	v_add_u32_e32 v14, 0xffffffac, v0
	v_cmp_le_i32_e64 s[16:17], v14, v184
	v_add_u32_e32 v14, 0xffffff91, v0
	s_nop 0
	v_cndmask_b32_e64 v103, v194, v103, s[16:17]
	v_cmp_le_i32_e64 s[16:17], v14, v184
	v_add_u32_e32 v14, 0xffffffb1, v0
	v_cmp_le_i32_e64 s[18:19], v14, v184
	v_add_u32_e32 v14, 0xffffff92, v0
	s_nop 0
	v_cndmask_b32_e64 v104, v194, v104, s[18:19]
	v_cmp_le_i32_e64 s[18:19], v14, v184
	v_add_u32_e32 v14, 0xffffffb2, v0
	v_cmp_le_i32_e64 s[20:21], v14, v184
	v_add_u32_e32 v14, 0xffffff93, v0
	s_nop 0
	v_cndmask_b32_e64 v105, v194, v105, s[20:21]
	v_cmp_le_i32_e64 s[20:21], v14, v184
	v_add_u32_e32 v14, 0xffffffb3, v0
	v_cmp_le_i32_e64 s[22:23], v14, v184
	v_add_u32_e32 v14, 0xffffff94, v0
	s_nop 0
	v_cndmask_b32_e64 v106, v194, v106, s[22:23]
	v_cmp_le_i32_e64 s[22:23], v14, v184
	v_add_u32_e32 v14, 0xffffffb4, v0
	v_cmp_le_i32_e64 s[24:25], v14, v184
	v_add_u32_e32 v14, 0xffffff99, v0
	s_nop 0
	v_cndmask_b32_e64 v107, v194, v107, s[24:25]
	v_cmp_le_i32_e64 s[24:25], v14, v184
	v_add_u32_e32 v14, 0xffffffb9, v0
	v_cmp_le_i32_e64 s[26:27], v14, v184
	v_add_u32_e32 v14, 0xffffff9a, v0
	s_nop 0
	v_cndmask_b32_e64 v108, v194, v108, s[26:27]
	v_cmp_le_i32_e64 s[26:27], v14, v184
	v_add_u32_e32 v14, 0xffffffba, v0
	v_cmp_le_i32_e64 s[28:29], v14, v184
	v_add_u32_e32 v14, 0xffffff9b, v0
	s_nop 0
	v_cndmask_b32_e64 v109, v194, v109, s[28:29]
	v_cmp_le_i32_e64 s[28:29], v14, v184
	v_add_u32_e32 v14, 0xffffffbb, v0
	v_cmp_le_i32_e64 s[30:31], v14, v184
	v_add_u32_e32 v14, 0xffffff9c, v0
	v_add_u32_e32 v0, 0xffffffbc, v0
	v_cndmask_b32_e64 v110, v194, v110, s[30:31]
	v_cmp_le_i32_e64 s[30:31], v14, v184
	v_cmp_gt_i32_e64 s[34:35], v0, v184
	s_and_saveexec_b64 s[48:49], s[34:35]
	v_mov_b32_e32 v111, s59
	s_or_b64 exec, exec, s[48:49]
	v_cndmask_b32_e64 v113, v194, v113, s[2:3]
	v_cndmask_b32_e32 v112, v194, v112, vcc
	v_cndmask_b32_e64 v114, v194, v114, s[4:5]
	v_cndmask_b32_e64 v115, v194, v115, s[6:7]
	v_cndmask_b32_e64 v116, v194, v116, s[8:9]
	v_cndmask_b32_e64 v117, v194, v117, s[10:11]
	v_cndmask_b32_e64 v118, v194, v118, s[12:13]
	v_cndmask_b32_e64 v119, v194, v119, s[14:15]
	v_cndmask_b32_e64 v120, v194, v120, s[16:17]
	v_cndmask_b32_e64 v121, v194, v121, s[18:19]
	v_cndmask_b32_e64 v122, v194, v122, s[20:21]
	v_cndmask_b32_e64 v123, v194, v123, s[22:23]
	v_cndmask_b32_e64 v124, v194, v124, s[24:25]
	v_cndmask_b32_e64 v125, v194, v125, s[26:27]
	v_cndmask_b32_e64 v126, v194, v126, s[28:29]
	v_cndmask_b32_e64 v127, v194, v127, s[30:31]

.LBB0_685:
	s_add_i32 s4, s67, 2
	s_and_b32 s4, s4, 2
	s_mulk_i32 s4, 0x3400
	v_add_u32_e32 v0, s4, v196
	ds_read_b128 v[2:5], v0
	ds_read_b128 v[6:9], v0 offset:6656
	s_mulk_i32 s71, 0x3400
	s_add_i32 s3, s71, 0
	s_xor_b32 s2, s69, 2
	v_add_u32_e32 v96, s3, v192
	s_mulk_i32 s2, 0x2400
	s_waitcnt vmcnt(5)
	ds_write_b128 v96, v[168:171]
	v_add_u32_e32 v96, s3, v185
	s_waitcnt vmcnt(4)
	ds_write_b128 v96, v[164:167] offset:128
	v_add_u32_e32 v96, s2, v193
	s_add_i32 s2, s67, 6
	s_min_i32 s2, s2, s66
	s_mov_b32 s3, s47
	v_add_u32_e32 v96, 0xd000, v96
	s_lshl_b64 s[4:5], s[2:3], 16
	s_lshl_b64 s[2:3], s[2:3], 12
	s_waitcnt vmcnt(3)
	ds_write2_b64 v96, v[160:161], v[162:163] offset1:2
	v_lshl_add_u64 v[98:99], v[186:187], 0, s[4:5]
	v_lshl_add_u64 v[100:101], v[188:189], 0, s[2:3]
	s_lshl_b64 s[2:3], s[46:47], 7
	global_load_dwordx4 v[168:171], v[98:99], off
	global_load_dwordx4 v[164:167], v[100:101], off
	v_lshl_add_u64 v[98:99], v[190:191], 0, s[2:3]
	global_load_dwordx4 v[160:163], v[98:99], off
	s_add_i32 s46, s67, 2
	s_cmp_ge_i32 s67, s65
	s_cbranch_scc1 .LBB0_696
	s_waitcnt lgkmcnt(1)
	v_mfma_f32_32x32x16_bf16 v[112:127], v[2:5], v[128:131], v[48:63]
	ds_read_b128 v[10:13], v0 offset:32
	ds_read_b128 v[202:205], v0 offset:6688
	v_add_f32_e32 v211, 0, v80
	v_add_f32_e32 v210, 0, v81
	v_cvt_pk_bf16_f32 v176, v80, v81
	s_waitcnt lgkmcnt(2)
	v_mfma_f32_32x32x16_bf16 v[96:111], v[6:9], v[128:131], v[48:63]
	v_add_f32_e32 v211, v82, v211
	v_add_f32_e32 v210, v83, v210
	v_add_f32_e32 v211, v84, v211
	v_cvt_pk_bf16_f32 v177, v82, v83
	s_waitcnt lgkmcnt(1)
	v_mfma_f32_32x32x16_bf16 v[112:127], v[10:13], v[132:135], v[112:127]
	ds_read_b128 v[2:5], v0 offset:64
	ds_read_b128 v[6:9], v0 offset:6720
	v_add_f32_e32 v210, v85, v210
	v_add_f32_e32 v211, v86, v211
	v_add_f32_e32 v210, v87, v210
	v_cvt_pk_bf16_f32 v178, v84, v85
	v_cvt_pk_bf16_f32 v179, v86, v87
	s_waitcnt lgkmcnt(2)
	v_mfma_f32_32x32x16_bf16 v[96:111], v[202:205], v[132:135], v[96:111]
	v_add_f32_e32 v211, v88, v211
	v_add_f32_e32 v210, v89, v210
	v_cvt_pk_bf16_f32 v10, v88, v89
	s_waitcnt lgkmcnt(1)
	v_mfma_f32_32x32x16_bf16 v[112:127], v[2:5], v[136:139], v[112:127]
	ds_read_b128 v[80:83], v0 offset:96
	ds_read_b128 v[202:205], v0 offset:6752
	v_add_f32_e32 v211, v90, v211
	v_add_f32_e32 v210, v91, v210
	v_add_f32_e32 v211, v92, v211
	v_cvt_pk_bf16_f32 v11, v90, v91
	s_waitcnt lgkmcnt(2)
	v_mfma_f32_32x32x16_bf16 v[96:111], v[6:9], v[136:139], v[96:111]
	v_add_f32_e32 v210, v93, v210
	v_add_f32_e32 v211, v94, v211
	v_add_f32_e32 v210, v95, v210
	v_cvt_pk_bf16_f32 v12, v92, v93
	v_cvt_pk_bf16_f32 v13, v94, v95
	s_waitcnt lgkmcnt(1)
	v_mfma_f32_32x32x16_bf16 v[112:127], v[80:83], v[140:143], v[112:127]
	ds_read_b128 v[2:5], v0 offset:128
	ds_read_b128 v[206:209], v0 offset:6784
	v_add_f32_e32 v211, v16, v211
	v_add_f32_e32 v210, v17, v210
	v_cvt_pk_bf16_f32 v6, v16, v17
	s_waitcnt lgkmcnt(2)
	v_mfma_f32_32x32x16_bf16 v[96:111], v[202:205], v[140:143], v[96:111]
	v_add_f32_e32 v211, v18, v211
	v_add_f32_e32 v210, v19, v210
	v_add_f32_e32 v211, v20, v211
	v_cvt_pk_bf16_f32 v7, v18, v19
	s_waitcnt lgkmcnt(1)
	v_mfma_f32_32x32x16_bf16 v[112:127], v[2:5], v[144:147], v[112:127]
	ds_read_b128 v[14:17], v0 offset:160
	ds_read_b128 v[80:83], v0 offset:6816
	v_add_f32_e32 v210, v21, v210
	v_add_f32_e32 v211, v22, v211
	v_add_f32_e32 v210, v23, v210
	v_cvt_pk_bf16_f32 v8, v20, v21
	v_cvt_pk_bf16_f32 v9, v22, v23
	s_waitcnt lgkmcnt(2)
	v_mfma_f32_32x32x16_bf16 v[96:111], v[206:209], v[144:147], v[96:111]
	v_add_f32_e32 v211, v24, v211
	v_add_f32_e32 v210, v25, v210
	v_cvt_pk_bf16_f32 v2, v24, v25
	s_waitcnt lgkmcnt(1)
	v_mfma_f32_32x32x16_bf16 v[112:127], v[14:17], v[148:151], v[112:127]
	v_add_f32_e32 v211, v26, v211
	v_add_f32_e32 v210, v27, v210
	v_add_f32_e32 v211, v28, v211
	v_cvt_pk_bf16_f32 v3, v26, v27
	s_waitcnt lgkmcnt(0)
	v_mfma_f32_32x32x16_bf16 v[96:111], v[80:83], v[148:151], v[96:111]
	v_add_f32_e32 v210, v29, v210
	v_add_f32_e32 v211, v30, v211
	v_add_f32_e32 v210, v31, v210
	v_add_f32_e32 v0, v210, v211
	v_cvt_pk_bf16_f32 v4, v28, v29
	v_cvt_pk_bf16_f32 v5, v30, v31
	s_mul_i32 s4, s69, 0x2400
	v_add_u32_e32 v206, s4, v200
	ds_read_b128 v[16:19], v206 offset:53248
	ds_read_b128 v[202:205], v206 offset:57856
	s_cmp_ge_i32 s70, s65
	v_add_f32_e32 v201, v201, v0
	s_cbranch_scc1 .LBB0_693
	s_cmp_le_i32 s68, s63
	s_cbranch_scc1 .LBB0_691
	v_add_u32_e32 v0, s68, v197
	v_subrev_u32_e32 v15, 31, v0
	v_subrev_u32_e32 v14, 63, v0
	v_cmp_le_i32_e64 s[2:3], v15, v184
	v_cmp_le_i32_e32 vcc, v14, v184
	s_nop 0
	v_cndmask_b32_e64 v96, v194, v96, s[2:3]
	v_cmp_lt_i32_e64 s[2:3], v14, v184
	v_subrev_u32_e32 v14, 30, v0
	v_cmp_le_i32_e64 s[4:5], v14, v184
	v_subrev_u32_e32 v14, 61, v0
	s_nop 0
	v_cndmask_b32_e64 v97, v194, v97, s[4:5]
	v_cmp_le_i32_e64 s[4:5], v14, v184
	v_subrev_u32_e32 v14, 29, v0
	v_cmp_le_i32_e64 s[6:7], v14, v184
	v_subrev_u32_e32 v14, 60, v0
	s_nop 0
	v_cndmask_b32_e64 v98, v194, v98, s[6:7]
	v_cmp_le_i32_e64 s[6:7], v14, v184
	v_subrev_u32_e32 v14, 28, v0
	v_cmp_le_i32_e64 s[8:9], v14, v184
	v_subrev_u32_e32 v14, 55, v0
	s_nop 0
	v_cndmask_b32_e64 v99, v194, v99, s[8:9]
	v_cmp_le_i32_e64 s[8:9], v14, v184
	v_subrev_u32_e32 v14, 23, v0
	v_cmp_le_i32_e64 s[10:11], v14, v184
	v_subrev_u32_e32 v14, 54, v0
	s_nop 0
	v_cndmask_b32_e64 v100, v194, v100, s[10:11]
	v_cmp_le_i32_e64 s[10:11], v14, v184
	v_subrev_u32_e32 v14, 22, v0
	v_cmp_le_i32_e64 s[12:13], v14, v184
	v_subrev_u32_e32 v14, 53, v0
	s_nop 0
	v_cndmask_b32_e64 v101, v194, v101, s[12:13]
	v_cmp_le_i32_e64 s[12:13], v14, v184
	v_subrev_u32_e32 v14, 21, v0
	v_cmp_le_i32_e64 s[14:15], v14, v184
	v_subrev_u32_e32 v14, 52, v0
	s_nop 0
	v_cndmask_b32_e64 v102, v194, v102, s[14:15]
	v_cmp_le_i32_e64 s[14:15], v14, v184
	v_subrev_u32_e32 v14, 20, v0
	v_cmp_le_i32_e64 s[16:17], v14, v184
	v_subrev_u32_e32 v14, 47, v0
	s_nop 0
	v_cndmask_b32_e64 v103, v194, v103, s[16:17]
	v_cmp_le_i32_e64 s[16:17], v14, v184
	v_add_u32_e32 v14, -15, v0
	v_cmp_le_i32_e64 s[18:19], v14, v184
	v_subrev_u32_e32 v14, 46, v0
	s_nop 0
	v_cndmask_b32_e64 v104, v194, v104, s[18:19]
	v_cmp_le_i32_e64 s[18:19], v14, v184
	v_add_u32_e32 v14, -14, v0
	v_cmp_le_i32_e64 s[20:21], v14, v184
	v_subrev_u32_e32 v14, 45, v0
	s_nop 0
	v_cndmask_b32_e64 v105, v194, v105, s[20:21]
	v_cmp_le_i32_e64 s[20:21], v14, v184
	v_add_u32_e32 v14, -13, v0
	v_cmp_le_i32_e64 s[22:23], v14, v184
	v_subrev_u32_e32 v14, 44, v0
	s_nop 0
	v_cndmask_b32_e64 v106, v194, v106, s[22:23]
	v_cmp_le_i32_e64 s[22:23], v14, v184
	v_add_u32_e32 v14, -12, v0
	v_cmp_le_i32_e64 s[24:25], v14, v184
	v_subrev_u32_e32 v14, 39, v0
	s_nop 0
	v_cndmask_b32_e64 v107, v194, v107, s[24:25]
	v_cmp_le_i32_e64 s[24:25], v14, v184
	v_add_u32_e32 v14, -7, v0
	v_cmp_le_i32_e64 s[26:27], v14, v184
	v_subrev_u32_e32 v14, 38, v0
	s_nop 0
	v_cndmask_b32_e64 v108, v194, v108, s[26:27]
	v_cmp_le_i32_e64 s[26:27], v14, v184
	v_add_u32_e32 v14, -6, v0
	v_cmp_le_i32_e64 s[28:29], v14, v184
	v_subrev_u32_e32 v14, 37, v0
	s_nop 0
	v_cndmask_b32_e64 v109, v194, v109, s[28:29]
	v_cmp_le_i32_e64 s[28:29], v14, v184
	v_add_u32_e32 v14, -5, v0
	v_cmp_le_i32_e64 s[30:31], v14, v184
	v_subrev_u32_e32 v14, 36, v0
	v_add_u32_e32 v0, -4, v0
	v_cndmask_b32_e64 v110, v194, v110, s[30:31]
	v_cmp_le_i32_e64 s[30:31], v14, v184
	v_cmp_gt_i32_e64 s[34:35], v0, v184
	s_and_saveexec_b64 s[48:49], s[34:35]
	v_mov_b32_e32 v111, s59
	s_or_b64 exec, exec, s[48:49]
	v_cndmask_b32_e64 v113, v194, v113, s[2:3]
	v_cndmask_b32_e32 v112, v194, v112, vcc
	v_cndmask_b32_e64 v114, v194, v114, s[4:5]
	v_cndmask_b32_e64 v115, v194, v115, s[6:7]
	v_cndmask_b32_e64 v116, v194, v116, s[8:9]
	v_cndmask_b32_e64 v117, v194, v117, s[10:11]
	v_cndmask_b32_e64 v118, v194, v118, s[12:13]
	v_cndmask_b32_e64 v119, v194, v119, s[14:15]
	v_cndmask_b32_e64 v120, v194, v120, s[16:17]
	v_cndmask_b32_e64 v121, v194, v121, s[18:19]
	v_cndmask_b32_e64 v122, v194, v122, s[20:21]
	v_cndmask_b32_e64 v123, v194, v123, s[22:23]
	v_cndmask_b32_e64 v124, v194, v124, s[24:25]
	v_cndmask_b32_e64 v125, v194, v125, s[26:27]
	v_cndmask_b32_e64 v126, v194, v126, s[28:29]
	v_cndmask_b32_e64 v127, v194, v127, s[30:31]
